# attention: K/V LDS staging writes moved to the head of the MFMA block (before QK)
# baseline (speedup 1.0000x reference)
; #define AT_STOREK(bf) do { *(LAS v4u*)(lds + (bf) * AT_KBUF + kso) = kr0; *(LAS v4u*)(lds + (bf) * AT_KBUF + kso + 32 * AT_KSTR * 2) = kr1; } while (0)
; #define AT_STOREV(bf) do { *(LAS v2u*)(lds + (bf) * AT_VBUF + vso) = (v2u){vr0.x, vr0.y}; *(LAS v2u*)(lds + (bf) * AT_VBUF + vso + 8) = (v2u){vr0.z, vr0.w}; \
;         *(LAS v2u*)(lds + (bf) * AT_VBUF + vso + 64 * AT_VSTR * 2) = (v2u){vr1.x, vr1.y}; *(LAS v2u*)(lds + (bf) * AT_VBUF + vso + 64 * AT_VSTR * 2 + 8) = (v2u){vr1.z, vr1.w}; } while (0)
;     ...
;             if (!(AMODE & 4) && t >= 1) { if (t + 1 < NT) AT_STOREK((t + 1) & 1); if (t < NT) AT_STOREV(t & 1); }
.Lattn_kvstore:
	s_add_i32 s47, s50, 1
	s_cmp_ge_i32 s47, s5
	s_cbranch_scc1 .Lattn_kvstore_v
	s_bitcmp1_b32 s47, 0
	s_cselect_b32 s49, 0x4400, 0
	v_add_u32_e32 v33, s49, v219
	s_waitcnt vmcnt(1)
	ds_write_b128 v33, v[160:163]
	s_waitcnt vmcnt(0)
	ds_write_b128 v33, v[164:167] offset:8704
.Lattn_kvstore_v:
	s_bitcmp1_b32 s50, 0
	s_cselect_b32 s49, 0x4400, 0
	v_add_u32_e32 v33, s49, v220
	v_add_u32_e32 v34, 0x8800, v33
	v_add_u32_e32 v33, 0xaa00, v33
	s_waitcnt vmcnt(1)
	ds_write2_b64 v34, v[168:169], v[170:171] offset1:1
	s_waitcnt vmcnt(0)
	ds_write2_b64 v33, v[172:173], v[174:175] offset1:1
	s_cmp_lt_i32 s50, s18
	s_cbranch_scc0 .LBB0_390

; #define AT_LOADK(t) do { kr0 = *(const v4u*)(kg + (size_t)(t) * 64 * 1024); kr1 = *(const v4u*)(kg + (size_t)(t) * 64 * 1024 + 32 * 1024); } while (0)
; #define AT_LOADV(t) do { vr0 = *(const v4u*)(vg + (t) * 64); vr1 = *(const v4u*)(vg + (size_t)64 * SEQ + (t) * 64); } while (0)
; #define AT_STOREK(bf) do { *(LAS v4u*)(lds + (bf) * AT_KBUF + kso) = kr0; *(LAS v4u*)(lds + (bf) * AT_KBUF + kso + 32 * AT_KSTR * 2) = kr1; } while (0)
; #define AT_STOREV(bf) do { *(LAS v2u*)(lds + (bf) * AT_VBUF + vso) = (v2u){vr0.x, vr0.y}; *(LAS v2u*)(lds + (bf) * AT_VBUF + vso + 8) = (v2u){vr0.z, vr0.w}; \
;         *(LAS v2u*)(lds + (bf) * AT_VBUF + vso + 64 * AT_VSTR * 2) = (v2u){vr1.x, vr1.y}; *(LAS v2u*)(lds + (bf) * AT_VBUF + vso + 64 * AT_VSTR * 2 + 8) = (v2u){vr1.z, vr1.w}; } while (0)
;     ...
;             if (!(AMODE & 4) && t >= 1) { if (t + 1 < NT) AT_STOREK((t + 1) & 1); if (t < NT) AT_STOREV(t & 1); }
;             __syncthreads();
;             if (!(AMODE & 4)) { if (t + 2 < NT) AT_LOADK(t + 2); if (t + 1 < NT) AT_LOADV(t + 1); }
.LBB0_393:
	s_waitcnt lgkmcnt(0)
	s_barrier
	s_setprio 1
	global_load_dwordx4 v[160:163], v[216:217], off
	s_mov_b64 s[66:67], 0x10000
	s_and_b64 vcc, exec, s[6:7]
	s_cbranch_vccz .LBB0_400

; #define AT_STOREK(bf) do { *(LAS v4u*)(lds + (bf) * AT_KBUF + kso) = kr0; *(LAS v4u*)(lds + (bf) * AT_KBUF + kso + 32 * AT_KSTR * 2) = kr1; } while (0)
; #define AT_STOREV(bf) do { *(LAS v2u*)(lds + (bf) * AT_VBUF + vso) = (v2u){vr0.x, vr0.y}; *(LAS v2u*)(lds + (bf) * AT_VBUF + vso + 8) = (v2u){vr0.z, vr0.w}; \
;         *(LAS v2u*)(lds + (bf) * AT_VBUF + vso + 64 * AT_VSTR * 2) = (v2u){vr1.x, vr1.y}; *(LAS v2u*)(lds + (bf) * AT_VBUF + vso + 64 * AT_VSTR * 2 + 8) = (v2u){vr1.z, vr1.w}; } while (0)
;     ...
;         for (int t = 0; t < NT; ++t) {
;     ...
;             if (!(AMODE & 4) && t >= 1) { if (t + 1 < NT) AT_STOREK((t + 1) & 1); if (t < NT) AT_STOREV(t & 1); }
.LBB0_469:
	s_sub_i32 s19, s19, 64
	s_add_i32 s94, s94, 64
	v_subrev_u32_e32 v251, 64, v251
	s_cmp_eq_u32 s47, s5
	v_lshl_add_u64 v[216:217], v[216:217], 0, s[12:13]
	s_cbranch_scc1 .LBB0_308
	s_mov_b32 s50, s47
	s_cmp_ge_i32 s50, s18
	s_cselect_b64 s[6:7], -1, 0
	s_branch .Lattn_kvstore
